# v86: mLSTM output pass, inter-chunk state term: 9 of the later n-vector loads issued with the first four (two memory round trips instead of five)
# speedup vs baseline: 1.0085x; 1.0076x over previous
.LBB0_9:
	s_mul_i32 s3, s6, 3
	s_getpc_b64 s[0:1]
	s_add_u32 s0, s0, PROG@rel32@lo+4
	s_addc_u32 s1, s1, PROG@rel32@hi+12
	s_and_b32 s2, s3, -4
	s_add_u32 s0, s0, s2
	s_addc_u32 s1, s1, 0
	s_load_dwordx2 s[0:1], s[0:1], 0x0
	s_and_b32 s3, s3, 3
	s_lshl_b32 s3, s3, 3
	s_waitcnt lgkmcnt(0)
	s_lshr_b64 s[0:1], s[0:1], s3
	s_and_b32 s2, s0, 0xffff
	v_mov_b32_e32 v0, s2
	s_bfe_u32 s2, s0, 0x80010
	v_mov_b32_e32 v2, s2
	s_cmp_gt_u32 s6, 1
	s_cbranch_scc1 .Lsm_done
	v_readlane_b32 s0, v254, 39
	v_readlane_b32 s1, v254, 40
	s_add_u32 s0, s0, 0xc000
	s_addc_u32 s1, s1, 0
	s_cmp_eq_u32 s6, 1
	s_cbranch_scc1 .Lsm_cache
	s_getreg_b32 s2, hwreg(HW_REG_XCC_ID, 0, 4)
	s_and_b32 s2, s2, 15
	s_lshl_b32 s2, 1, s2
	s_and_b32 s3, s66, 7
	s_lshl_b32 s3, s3, 2
	s_add_u32 s0, s0, s3
	s_addc_u32 s1, s1, 0
	v_mov_b32_e32 v3, s2
	s_mov_b64 s[2:3], exec
	s_mov_b64 exec, 1
	global_atomic_or v1, v3, s[0:1]
	s_mov_b64 exec, s[2:3]
	s_branch .Lsm_done
	s_nop 0
	s_nop 0
	s_nop 0
	s_nop 0
	s_nop 0
	s_nop 0
	s_nop 0
	s_nop 0
	s_nop 0
	s_nop 0
	s_nop 0
	s_nop 0
	s_nop 0
.Lsm_cache:
	global_load_dwordx4 v[4:7], v1, s[0:1] sc1
	global_load_dwordx4 v[8:11], v1, s[0:1] offset:16 sc1
	s_waitcnt vmcnt(0)
	v_add_u32_e32 v3, -1, v4
	v_and_b32_e32 v3, v3, v4
	v_add_u32_e32 v4, -1, v5
	v_and_or_b32 v3, v4, v5, v3
	v_add_u32_e32 v4, -1, v6
	v_and_or_b32 v3, v4, v6, v3
	v_add_u32_e32 v4, -1, v7
	v_and_or_b32 v3, v4, v7, v3
	v_add_u32_e32 v4, -1, v8
	v_and_or_b32 v3, v4, v8, v3
	v_add_u32_e32 v4, -1, v9
	v_and_or_b32 v3, v4, v9, v3
	v_add_u32_e32 v4, -1, v10
	v_and_or_b32 v3, v4, v10, v3
	v_add_u32_e32 v4, -1, v11
	v_and_or_b32 v3, v4, v11, v3
	s_nop 0
	v_readfirstlane_b32 s2, v3
	s_nop 1
	v_writelane_b32 v255, s2, 63

.LBB0_233:
	v_mov_b32_e32 v135, v187
	ds_read_b128 v[138:141], v190 offset:512
	v_sub_u32_e32 v135, v130, v135
	v_sub_u32_e32 v142, 0, v135
	v_cndmask_b32_e64 v142, v142, v135, s[42:43]
	v_max_i32_e32 v142, 0, v142
	v_cvt_f32_u32_e32 v142, v142
	s_waitcnt lgkmcnt(1)
	v_sub_f32_e32 v0, v136, v137
	s_waitcnt lgkmcnt(0)
	v_add_f32_e32 v138, v0, v138
	v_not_b32_e32 v143, v135
	v_fmac_f32_e32 v138, 0xf149f2ca, v142
	v_add_u32_e32 v142, 1, v135
	v_cndmask_b32_e64 v142, v143, v142, s[42:43]
	v_max_i32_e32 v142, 0, v142
	v_cvt_f32_u32_e32 v142, v142
	v_add_f32_e32 v139, v0, v139
	v_mul_f32_e32 v138, 0x3fb8aa3b, v138
	v_exp_f32_e32 v138, v138
	v_fmac_f32_e32 v139, 0xf149f2ca, v142
	v_mul_f32_e32 v139, 0x3fb8aa3b, v139
	v_exp_f32_e32 v139, v139
	v_add_u32_e32 v143, 16, v135
	v_sub_u32_e32 v144, -16, v135
	v_cndmask_b32_e64 v143, v144, v143, s[42:43]
	v_pk_mul_f32 v[126:127], v[126:127], v[138:139]
	v_sub_u32_e32 v139, -2, v135
	v_add_f32_e32 v138, 0, v126
	v_add_f32_e32 v142, v138, v127
	v_add_u32_e32 v138, 2, v135
	v_cndmask_b32_e64 v138, v139, v138, s[42:43]
	v_max_i32_e32 v138, 0, v138
	v_cvt_f32_u32_e32 v138, v138
	v_add_f32_e32 v139, v0, v140
	v_sub_u32_e32 v140, -3, v135
	v_max_i32_e32 v143, 0, v143
	v_fmac_f32_e32 v139, 0xf149f2ca, v138
	v_mul_f32_e32 v138, 0x3fb8aa3b, v139
	v_add_u32_e32 v139, 3, v135
	v_cndmask_b32_e64 v139, v140, v139, s[42:43]
	v_max_i32_e32 v139, 0, v139
	v_cvt_f32_u32_e32 v139, v139
	v_add_f32_e32 v140, v0, v141
	v_exp_f32_e32 v138, v138
	v_cvt_f32_u32_e32 v143, v143
	v_fmac_f32_e32 v140, 0xf149f2ca, v139
	v_mul_f32_e32 v139, 0x3fb8aa3b, v140
	v_exp_f32_e32 v139, v139
	v_sub_u32_e32 v144, 0xffffffef, v135
	s_and_b64 vcc, exec, s[34:35]
	v_pk_mul_f32 v[128:129], v[128:129], v[138:139]
	s_nop 0
	v_add_f32_e32 v138, v128, v142
	v_add_f32_e32 v142, v129, v138
	ds_read_b128 v[138:141], v190 offset:576
	s_waitcnt lgkmcnt(0)
	v_add_f32_e32 v138, v0, v138
	v_fmac_f32_e32 v138, 0xf149f2ca, v143
	v_add_u32_e32 v143, 17, v135
	v_cndmask_b32_e64 v143, v144, v143, s[42:43]
	v_max_i32_e32 v143, 0, v143
	v_cvt_f32_u32_e32 v143, v143
	v_add_f32_e32 v139, v0, v139
	v_mul_f32_e32 v138, 0x3fb8aa3b, v138
	v_exp_f32_e32 v138, v138
	v_fmac_f32_e32 v139, 0xf149f2ca, v143
	v_mul_f32_e32 v139, 0x3fb8aa3b, v139
	v_exp_f32_e32 v139, v139
	v_add_u32_e32 v143, 32, v135
	v_sub_u32_e32 v144, 0xffffffe0, v135
	v_cndmask_b32_e64 v143, v144, v143, s[42:43]
	v_pk_mul_f32 v[118:119], v[118:119], v[138:139]
	v_sub_u32_e32 v139, 0xffffffee, v135
	v_add_f32_e32 v138, v118, v142
	v_add_f32_e32 v142, v119, v138
	v_add_u32_e32 v138, 18, v135
	v_cndmask_b32_e64 v138, v139, v138, s[42:43]
	v_max_i32_e32 v138, 0, v138
	v_cvt_f32_u32_e32 v138, v138
	v_add_f32_e32 v139, v0, v140
	v_sub_u32_e32 v140, 0xffffffed, v135
	v_max_i32_e32 v143, 0, v143
	v_fmac_f32_e32 v139, 0xf149f2ca, v138
	v_mul_f32_e32 v138, 0x3fb8aa3b, v139
	v_add_u32_e32 v139, 19, v135
	v_cndmask_b32_e64 v139, v140, v139, s[42:43]
	v_max_i32_e32 v139, 0, v139
	v_cvt_f32_u32_e32 v139, v139
	v_add_f32_e32 v140, v0, v141
	v_exp_f32_e32 v138, v138
	v_cvt_f32_u32_e32 v143, v143
	v_fmac_f32_e32 v140, 0xf149f2ca, v139
	v_mul_f32_e32 v139, 0x3fb8aa3b, v140
	v_exp_f32_e32 v139, v139
	v_sub_u32_e32 v144, 0xffffffdf, v135
	v_pk_mul_f32 v[120:121], v[120:121], v[138:139]
	s_nop 0
	v_add_f32_e32 v138, v120, v142
	v_add_f32_e32 v142, v121, v138
	ds_read_b128 v[138:141], v190 offset:640
	s_waitcnt lgkmcnt(0)
	v_add_f32_e32 v138, v0, v138
	v_fmac_f32_e32 v138, 0xf149f2ca, v143
	v_add_u32_e32 v143, 33, v135
	v_cndmask_b32_e64 v143, v144, v143, s[42:43]
	v_max_i32_e32 v143, 0, v143
	v_cvt_f32_u32_e32 v143, v143
	v_add_f32_e32 v139, v0, v139
	v_mul_f32_e32 v138, 0x3fb8aa3b, v138
	v_exp_f32_e32 v138, v138
	v_fmac_f32_e32 v139, 0xf149f2ca, v143
	v_mul_f32_e32 v139, 0x3fb8aa3b, v139
	v_exp_f32_e32 v139, v139
	v_add_u32_e32 v143, 48, v135
	v_sub_u32_e32 v144, 0xffffffd0, v135
	v_cndmask_b32_e64 v143, v144, v143, s[42:43]
	v_pk_mul_f32 v[122:123], v[122:123], v[138:139]
	v_sub_u32_e32 v139, 0xffffffde, v135
	v_add_f32_e32 v138, v122, v142
	v_add_f32_e32 v142, v123, v138
	v_add_u32_e32 v138, 34, v135
	v_cndmask_b32_e64 v138, v139, v138, s[42:43]
	v_max_i32_e32 v138, 0, v138
	v_cvt_f32_u32_e32 v138, v138
	v_add_f32_e32 v139, v0, v140
	v_sub_u32_e32 v140, 0xffffffdd, v135
	v_max_i32_e32 v143, 0, v143
	v_fmac_f32_e32 v139, 0xf149f2ca, v138
	v_mul_f32_e32 v138, 0x3fb8aa3b, v139
	v_add_u32_e32 v139, 35, v135
	v_cndmask_b32_e64 v139, v140, v139, s[42:43]
	v_max_i32_e32 v139, 0, v139
	v_cvt_f32_u32_e32 v139, v139
	v_add_f32_e32 v140, v0, v141
	v_exp_f32_e32 v138, v138
	v_cvt_f32_u32_e32 v143, v143
	v_fmac_f32_e32 v140, 0xf149f2ca, v139
	v_mul_f32_e32 v139, 0x3fb8aa3b, v140
	v_exp_f32_e32 v139, v139
	v_sub_u32_e32 v144, 0xffffffcf, v135
	v_pk_mul_f32 v[124:125], v[124:125], v[138:139]
	s_nop 0
	v_add_f32_e32 v138, v124, v142
	v_add_f32_e32 v142, v125, v138
	ds_read_b128 v[138:141], v190 offset:704
	s_waitcnt lgkmcnt(0)
	v_add_f32_e32 v138, v0, v138
	v_fmac_f32_e32 v138, 0xf149f2ca, v143
	v_add_u32_e32 v143, 49, v135
	v_cndmask_b32_e64 v143, v144, v143, s[42:43]
	v_max_i32_e32 v143, 0, v143
	v_cvt_f32_u32_e32 v143, v143
	v_add_f32_e32 v139, v0, v139
	v_mul_f32_e32 v138, 0x3fb8aa3b, v138
	v_exp_f32_e32 v138, v138
	v_fmac_f32_e32 v139, 0xf149f2ca, v143
	v_mul_f32_e32 v139, 0x3fb8aa3b, v139
	v_exp_f32_e32 v139, v139
	v_add_u32_e32 v143, 64, v135
	v_sub_u32_e32 v144, 0xffffffc0, v135
	v_cndmask_b32_e64 v143, v144, v143, s[42:43]
	v_pk_mul_f32 v[138:139], v[110:111], v[138:139]
	v_sub_u32_e32 v111, 0xffffffce, v135
	v_add_f32_e32 v110, v138, v142
	v_add_f32_e32 v142, v139, v110
	v_add_u32_e32 v110, 50, v135
	v_cndmask_b32_e64 v110, v111, v110, s[42:43]
	v_max_i32_e32 v110, 0, v110
	v_cvt_f32_u32_e32 v110, v110
	v_add_f32_e32 v111, v0, v140
	v_sub_u32_e32 v140, 0xffffffcd, v135
	v_max_i32_e32 v143, 0, v143
	v_fmac_f32_e32 v111, 0xf149f2ca, v110
	v_mul_f32_e32 v110, 0x3fb8aa3b, v111
	v_add_u32_e32 v111, 51, v135
	v_cndmask_b32_e64 v111, v140, v111, s[42:43]
	v_max_i32_e32 v111, 0, v111
	v_cvt_f32_u32_e32 v111, v111
	v_add_f32_e32 v140, v0, v141
	v_exp_f32_e32 v110, v110
	v_cvt_f32_u32_e32 v143, v143
	v_fmac_f32_e32 v140, 0xf149f2ca, v111
	v_mul_f32_e32 v111, 0x3fb8aa3b, v140
	v_exp_f32_e32 v111, v111
	v_sub_u32_e32 v144, 0xffffffbf, v135
	v_pk_mul_f32 v[140:141], v[112:113], v[110:111]
	s_nop 0
	v_add_f32_e32 v110, v140, v142
	v_add_f32_e32 v142, v141, v110
	ds_read_b128 v[110:113], v190 offset:768
	s_waitcnt lgkmcnt(0)
	v_add_f32_e32 v110, v0, v110
	v_fmac_f32_e32 v110, 0xf149f2ca, v143
	v_add_u32_e32 v143, 0x41, v135
	v_cndmask_b32_e64 v143, v144, v143, s[42:43]
	v_max_i32_e32 v143, 0, v143
	v_cvt_f32_u32_e32 v143, v143
	v_add_f32_e32 v111, v0, v111
	v_mul_f32_e32 v110, 0x3fb8aa3b, v110
	v_exp_f32_e32 v110, v110
	v_fmac_f32_e32 v111, 0xf149f2ca, v143
	v_mul_f32_e32 v111, 0x3fb8aa3b, v111
	v_exp_f32_e32 v111, v111
	v_sub_u32_e32 v143, 0xffffffb0, v135
	v_pk_mul_f32 v[114:115], v[114:115], v[110:111]
	s_nop 0
	v_add_f32_e32 v110, v114, v142
	v_add_f32_e32 v142, v115, v110
	v_add_u32_e32 v110, 0x42, v135
	v_sub_u32_e32 v111, 0xffffffbe, v135
	v_cndmask_b32_e64 v110, v111, v110, s[42:43]
	v_max_i32_e32 v110, 0, v110
	v_cvt_f32_u32_e32 v110, v110
	v_add_f32_e32 v111, v0, v112
	v_sub_u32_e32 v112, 0xffffffbd, v135
	v_fmac_f32_e32 v111, 0xf149f2ca, v110
	v_mul_f32_e32 v110, 0x3fb8aa3b, v111
	v_add_u32_e32 v111, 0x43, v135
	v_cndmask_b32_e64 v111, v112, v111, s[42:43]
	v_max_i32_e32 v111, 0, v111
	v_cvt_f32_u32_e32 v111, v111
	v_add_f32_e32 v112, v0, v113
	v_exp_f32_e32 v110, v110
	v_fmac_f32_e32 v112, 0xf149f2ca, v111
	v_mul_f32_e32 v111, 0x3fb8aa3b, v112
	v_exp_f32_e32 v111, v111
	s_nop 0
	v_pk_mul_f32 v[116:117], v[116:117], v[110:111]
	s_nop 0
	v_add_f32_e32 v110, v116, v142
	v_add_u32_e32 v142, 0x50, v135
	v_add_f32_e32 v144, v117, v110
	ds_read_b128 v[110:113], v190 offset:832
	v_cndmask_b32_e64 v142, v143, v142, s[42:43]
	v_max_i32_e32 v142, 0, v142
	v_cvt_f32_u32_e32 v142, v142
	v_sub_u32_e32 v143, 0xffffffaf, v135
	s_waitcnt lgkmcnt(0)
	v_add_f32_e32 v110, v0, v110
	v_add_f32_e32 v111, v0, v111
	v_fmac_f32_e32 v110, 0xf149f2ca, v142
	v_add_u32_e32 v142, 0x51, v135
	v_cndmask_b32_e64 v142, v143, v142, s[42:43]
	v_max_i32_e32 v142, 0, v142
	v_cvt_f32_u32_e32 v142, v142
	v_mul_f32_e32 v110, 0x3fb8aa3b, v110
	v_exp_f32_e32 v110, v110
	v_fmac_f32_e32 v111, 0xf149f2ca, v142
	v_mul_f32_e32 v111, 0x3fb8aa3b, v111
	v_exp_f32_e32 v111, v111
	s_nop 0
	v_pk_mul_f32 v[142:143], v[102:103], v[110:111]
	s_nop 0
	v_add_f32_e32 v102, v142, v144
	v_add_f32_e32 v110, v143, v102
	v_add_u32_e32 v102, 0x52, v135
	v_sub_u32_e32 v103, 0xffffffae, v135
	v_cndmask_b32_e64 v102, v103, v102, s[42:43]
	v_max_i32_e32 v102, 0, v102
	v_cvt_f32_u32_e32 v102, v102
	v_add_f32_e32 v103, v0, v112
	v_sub_u32_e32 v111, 0xffffffad, v135
	v_sub_u32_e32 v112, 0xffffffa0, v135
	v_fmac_f32_e32 v103, 0xf149f2ca, v102
	v_mul_f32_e32 v102, 0x3fb8aa3b, v103
	v_add_u32_e32 v103, 0x53, v135
	v_cndmask_b32_e64 v103, v111, v103, s[42:43]
	v_max_i32_e32 v103, 0, v103
	v_cvt_f32_u32_e32 v103, v103
	v_add_f32_e32 v111, v0, v113
	v_exp_f32_e32 v102, v102
	v_fmac_f32_e32 v111, 0xf149f2ca, v103
	v_mul_f32_e32 v103, 0x3fb8aa3b, v111
	v_exp_f32_e32 v103, v103
	v_add_u32_e32 v111, 0x60, v135
	v_cndmask_b32_e64 v111, v112, v111, s[42:43]
	v_max_i32_e32 v111, 0, v111
	v_pk_mul_f32 v[144:145], v[104:105], v[102:103]
	v_cvt_f32_u32_e32 v111, v111
	v_add_f32_e32 v102, v144, v110
	v_add_f32_e32 v110, v145, v102
	ds_read_b128 v[102:105], v190 offset:896
	v_sub_u32_e32 v112, 0xffffff9f, v135
	s_waitcnt lgkmcnt(0)
	v_add_f32_e32 v102, v0, v102
	v_fmac_f32_e32 v102, 0xf149f2ca, v111
	v_add_u32_e32 v111, 0x61, v135
	v_cndmask_b32_e64 v111, v112, v111, s[42:43]
	v_max_i32_e32 v111, 0, v111
	v_cvt_f32_u32_e32 v111, v111
	v_add_f32_e32 v103, v0, v103
	v_mul_f32_e32 v102, 0x3fb8aa3b, v102
	v_exp_f32_e32 v102, v102
	v_fmac_f32_e32 v103, 0xf149f2ca, v111
	v_mul_f32_e32 v103, 0x3fb8aa3b, v103
	v_exp_f32_e32 v103, v103
	s_nop 0
	v_pk_mul_f32 v[146:147], v[106:107], v[102:103]
	s_nop 0
	v_add_f32_e32 v102, v146, v110
	v_add_f32_e32 v106, v147, v102
	v_add_u32_e32 v102, 0x62, v135
	v_sub_u32_e32 v103, 0xffffff9e, v135
	v_cndmask_b32_e64 v102, v103, v102, s[42:43]
	v_max_i32_e32 v102, 0, v102
	v_cvt_f32_u32_e32 v102, v102
	v_add_f32_e32 v103, v0, v104
	v_sub_u32_e32 v104, 0xffffff9d, v135
	v_add_u32_e32 v107, 0x70, v135
	v_fmac_f32_e32 v103, 0xf149f2ca, v102
	v_mul_f32_e32 v102, 0x3fb8aa3b, v103
	v_add_u32_e32 v103, 0x63, v135
	v_cndmask_b32_e64 v103, v104, v103, s[42:43]
	v_max_i32_e32 v103, 0, v103
	v_cvt_f32_u32_e32 v103, v103
	v_add_f32_e32 v104, v0, v105
	v_exp_f32_e32 v102, v102
	v_fmac_f32_e32 v104, 0xf149f2ca, v103
	v_mul_f32_e32 v103, 0x3fb8aa3b, v104
	v_exp_f32_e32 v103, v103
	s_nop 0
	v_pk_mul_f32 v[148:149], v[108:109], v[102:103]
	s_nop 0
	v_add_f32_e32 v102, v148, v106
	v_sub_u32_e32 v108, 0xffffff90, v135
	v_add_f32_e32 v106, v149, v102
	ds_read_b128 v[102:105], v190 offset:960
	v_cndmask_b32_e64 v107, v108, v107, s[42:43]
	v_max_i32_e32 v107, 0, v107
	v_cvt_f32_u32_e32 v107, v107
	v_sub_u32_e32 v108, 0xffffff8f, v135
	s_waitcnt lgkmcnt(0)
	v_add_f32_e32 v102, v0, v102
	v_add_f32_e32 v103, v0, v103
	v_fmac_f32_e32 v102, 0xf149f2ca, v107
	v_add_u32_e32 v107, 0x71, v135
	v_cndmask_b32_e64 v107, v108, v107, s[42:43]
	v_max_i32_e32 v107, 0, v107
	v_cvt_f32_u32_e32 v107, v107
	v_mul_f32_e32 v102, 0x3fb8aa3b, v102
	v_exp_f32_e32 v102, v102
	v_fmac_f32_e32 v103, 0xf149f2ca, v107
	v_mul_f32_e32 v103, 0x3fb8aa3b, v103
	v_exp_f32_e32 v103, v103
	s_nop 0
	v_pk_mul_f32 v[150:151], v[98:99], v[102:103]
	v_add_u32_e32 v98, 0x72, v135
	v_sub_u32_e32 v99, 0xffffff8e, v135
	v_cndmask_b32_e64 v98, v99, v98, s[42:43]
	v_max_i32_e32 v98, 0, v98
	v_cvt_f32_u32_e32 v98, v98
	v_add_f32_e32 v99, v0, v104
	v_sub_u32_e32 v102, 0xffffff8d, v135
	v_add_f32_e32 v0, v0, v105
	v_fmac_f32_e32 v99, 0xf149f2ca, v98
	v_mul_f32_e32 v98, 0x3fb8aa3b, v99
	v_add_u32_e32 v99, 0x73, v135
	v_cndmask_b32_e64 v99, v102, v99, s[42:43]
	v_max_i32_e32 v99, 0, v99
	v_cvt_f32_u32_e32 v99, v99
	v_exp_f32_e32 v98, v98
	v_fmac_f32_e32 v0, 0xf149f2ca, v99
	v_mul_f32_e32 v0, 0x3fb8aa3b, v0
	v_exp_f32_e32 v99, v0
	v_add_f32_e32 v0, v150, v106
	v_add_f32_e32 v0, v151, v0
	v_pk_mul_f32 v[152:153], v[100:101], v[98:99]
	s_nop 0
	v_add_f32_e32 v0, v152, v0
	v_add_f32_e32 v0, v153, v0
	ds_bpermute_b32 v98, v171, v0
	s_waitcnt lgkmcnt(0)
	v_add_f32_e32 v193, v0, v98
	ds_bpermute_b32 v194, v170, v193
	s_cbranch_vccnz .LBB0_235
	v_lshl_add_u64 v[110:111], v[132:133], 2, s[48:49]
	global_load_dwordx4 v[98:101], v[110:111], off offset:16
	global_load_dwordx4 v[102:105], v[110:111], off
	global_load_dwordx4 v[106:109], v[110:111], off offset:144
	global_load_dwordx4 v[154:157], v[110:111], off offset:128
	global_load_dwordx4 v[204:207], v[110:111], off offset:272
	global_load_dwordx4 v[208:211], v[110:111], off offset:256
	global_load_dwordx4 v[212:215], v[110:111], off offset:400
	global_load_dwordx4 v[216:219], v[110:111], off offset:384
	global_load_dwordx4 v[220:223], v[110:111], off offset:528
	global_load_dwordx4 v[236:239], v[110:111], off offset:512
	global_load_dwordx4 v[240:243], v[110:111], off offset:656
	global_load_dwordx4 v[244:247], v[110:111], off offset:640
	global_load_dwordx4 v[248:251], v[110:111], off offset:784
	s_waitcnt vmcnt(19)
	v_and_b32_e32 v161, 0xffff0000, v90
	v_and_b32_e32 v160, 0xffff0000, v94
	v_lshlrev_b32_e32 v113, 16, v90
	v_lshlrev_b32_e32 v112, 16, v94
	s_waitcnt vmcnt(11)
	v_mov_b32_e32 v158, v102
	s_waitcnt vmcnt(9)
	v_mov_b32_e32 v159, v154
	v_mov_b32_e32 v154, v103
	v_pk_mul_f32 v[102:103], v[154:155], v[160:161]
	v_mov_b32_e32 v155, v156
	v_pk_fma_f32 v[102:103], v[158:159], v[112:113], v[102:103]
	v_and_b32_e32 v159, 0xffff0000, v91
	v_and_b32_e32 v158, 0xffff0000, v95
	v_mov_b32_e32 v156, v105
	v_lshlrev_b32_e32 v113, 16, v91
	v_lshlrev_b32_e32 v112, 16, v95
	v_mov_b32_e32 v154, v104
	v_pk_mul_f32 v[104:105], v[156:157], v[158:159]
	v_and_b32_e32 v161, 0xffff0000, v82
	v_pk_fma_f32 v[104:105], v[154:155], v[112:113], v[104:105]
	v_mov_b32_e32 v113, v106
	v_and_b32_e32 v155, 0xffff0000, v92
	v_and_b32_e32 v154, 0xffff0000, v96
	v_mov_b32_e32 v106, v99
	v_pk_add_f32 v[102:103], v[102:103], v[104:105]
	v_lshlrev_b32_e32 v105, 16, v92
	v_lshlrev_b32_e32 v104, 16, v96
	v_mov_b32_e32 v112, v98
	v_pk_mul_f32 v[98:99], v[106:107], v[154:155]
	v_and_b32_e32 v107, 0xffff0000, v93
	v_pk_fma_f32 v[98:99], v[112:113], v[104:105], v[98:99]
	v_mov_b32_e32 v105, v108
	v_and_b32_e32 v106, 0xffff0000, v97
	v_mov_b32_e32 v108, v101
	v_pk_add_f32 v[98:99], v[98:99], v[102:103]
	v_lshlrev_b32_e32 v103, 16, v93
	v_lshlrev_b32_e32 v102, 16, v97
	v_mov_b32_e32 v104, v100
	v_pk_mul_f32 v[100:101], v[108:109], v[106:107]
	v_lshlrev_b32_e32 v154, 16, v86
	v_pk_fma_f32 v[100:101], v[104:105], v[102:103], v[100:101]
	v_and_b32_e32 v155, 0xffff0000, v87
	v_pk_add_f32 v[98:99], v[100:101], v[98:99]
	v_and_b32_e32 v106, 0xffff0000, v86
	v_add_f32_e32 v0, 0, v98
	v_add_f32_e32 v112, v0, v99
	s_waitcnt vmcnt(0)
	v_mov_b32_e32 v98, v204
	v_mov_b32_e32 v99, v205
	v_mov_b32_e32 v100, v206
	v_mov_b32_e32 v101, v207
	v_mov_b32_e32 v102, v208
	v_mov_b32_e32 v103, v209
	v_mov_b32_e32 v104, v210
	v_mov_b32_e32 v105, v211
	v_lshlrev_b32_e32 v107, 16, v87
	v_lshlrev_b32_e32 v0, 16, v79
	v_lshlrev_b32_e32 v160, 16, v82
	v_and_b32_e32 v159, 0xffff0000, v83
	v_lshlrev_b32_e32 v158, 16, v83
	v_mov_b32_e32 v108, v103
	v_mov_b32_e32 v103, v105
	v_mov_b32_e32 v109, v104
	v_pk_mul_f32 v[102:103], v[102:103], v[154:155]
	v_lshlrev_b32_e32 v105, 16, v89
	v_pk_fma_f32 v[102:103], v[108:109], v[106:107], v[102:103]
	v_mov_b32_e32 v107, v100
	v_and_b32_e32 v109, 0xffff0000, v89
	v_and_b32_e32 v108, 0xffff0000, v88
	v_mov_b32_e32 v100, v99
	v_lshlrev_b32_e32 v104, 16, v88
	v_mov_b32_e32 v106, v98
	v_pk_mul_f32 v[98:99], v[100:101], v[108:109]
	v_pk_add_f32 v[102:103], v[102:103], v[102:103] op_sel:[0,1] op_sel_hi:[1,0]
	v_pk_fma_f32 v[154:155], v[106:107], v[104:105], v[98:99]
	v_mov_b32_e32 v98, v212
	v_mov_b32_e32 v99, v213
	v_mov_b32_e32 v100, v214
	v_mov_b32_e32 v101, v215
	v_mov_b32_e32 v106, v216
	v_mov_b32_e32 v107, v217
	v_mov_b32_e32 v108, v218
	v_mov_b32_e32 v109, v219
	v_pk_add_f32 v[156:157], v[154:155], v[102:103]
	v_mov_b32_e32 v102, v220
	v_mov_b32_e32 v103, v221
	v_mov_b32_e32 v104, v222
	v_mov_b32_e32 v105, v223
	v_mov_b32_e32 v196, v236
	v_mov_b32_e32 v197, v237
	v_mov_b32_e32 v198, v238
	v_mov_b32_e32 v199, v239
	v_mov_b32_e32 v162, v98
	v_mul_f32_e32 v135, v198, v0
	v_and_b32_e32 v0, 0xffff0000, v79
	v_mul_f32_e32 v195, v199, v0
	v_lshlrev_b32_e32 v0, 16, v81
	v_mul_f32_e32 v113, v104, v0
	v_and_b32_e32 v0, 0xffff0000, v81
	v_mov_b32_e32 v163, v196
	v_and_b32_e32 v199, 0xffff0000, v78
	v_and_b32_e32 v198, 0xffff0000, v84
	v_mov_b32_e32 v196, v99
	v_mul_f32_e32 v200, v105, v0
	v_lshlrev_b32_e32 v105, 16, v78
	v_lshlrev_b32_e32 v104, 16, v84
	v_pk_mul_f32 v[98:99], v[196:197], v[198:199]
	v_mul_f32_e32 v0, v107, v161
	v_pk_fma_f32 v[98:99], v[162:163], v[104:105], v[98:99]
	v_pk_fma_f32 v[104:105], v[106:107], v[160:161], v[0:1] op_sel_hi:[1,1,0]
	v_mul_f32_e32 v0, v109, v159
	v_pk_fma_f32 v[106:107], v[108:109], v[158:159], v[0:1] op_sel_hi:[1,1,0]
	v_mov_b32_e32 v105, v135
	v_mov_b32_e32 v107, v195
	v_pk_add_f32 v[104:105], v[104:105], v[106:107]
	v_mov_b32_e32 v109, v102
	v_pk_add_f32 v[98:99], v[98:99], v[104:105]
	v_pk_mov_b32 v[104:105], v[84:85], v[80:81] op_sel:[1,0]
	v_mov_b32_e32 v102, v101
	v_and_b32_e32 v105, 0xffff0000, v105
	v_and_b32_e32 v104, 0xffff0000, v104
	v_lshlrev_b32_e32 v107, 16, v80
	v_lshlrev_b32_e32 v106, 16, v85
	v_mov_b32_e32 v108, v100
	v_pk_mul_f32 v[100:101], v[102:103], v[104:105]
	v_lshlrev_b32_e32 v0, 16, v67
	v_pk_fma_f32 v[100:101], v[108:109], v[106:107], v[100:101]
	v_and_b32_e32 v106, 0xffff0000, v74
	v_pk_add_f32 v[98:99], v[100:101], v[98:99]
	v_pk_add_f32 v[100:101], v[154:155], v[156:157] op_sel:[1,0] op_sel_hi:[0,1]
	v_mov_b32_e32 v101, v200
	v_pk_add_f32 v[100:101], v[112:113], v[100:101]
	v_lshlrev_b32_e32 v112, 16, v74
	v_pk_add_f32 v[154:155], v[100:101], v[98:99]
	v_mov_b32_e32 v98, v240
	v_mov_b32_e32 v99, v241
	v_mov_b32_e32 v100, v242
	v_mov_b32_e32 v101, v243
	v_mov_b32_e32 v102, v244
	v_mov_b32_e32 v103, v245
	v_mov_b32_e32 v104, v246
	v_mov_b32_e32 v105, v247
	v_and_b32_e32 v113, 0xffff0000, v75
	v_lshlrev_b32_e32 v107, 16, v75
	v_and_b32_e32 v163, 0xffff0000, v70
	v_lshlrev_b32_e32 v162, 16, v70
	v_and_b32_e32 v161, 0xffff0000, v71
	v_lshlrev_b32_e32 v160, 16, v71
	v_and_b32_e32 v197, 0xffff0000, v66
	v_and_b32_e32 v196, 0xffff0000, v72
	v_mov_b32_e32 v108, v103
	v_mov_b32_e32 v103, v105
	v_mov_b32_e32 v109, v104
	v_pk_mul_f32 v[102:103], v[102:103], v[112:113]
	v_lshlrev_b32_e32 v105, 16, v77
	v_pk_fma_f32 v[102:103], v[108:109], v[106:107], v[102:103]
	v_mov_b32_e32 v107, v100
	v_and_b32_e32 v109, 0xffff0000, v77
	v_and_b32_e32 v108, 0xffff0000, v76
	v_mov_b32_e32 v100, v99
	v_lshlrev_b32_e32 v104, 16, v76
	v_mov_b32_e32 v106, v98
	v_pk_mul_f32 v[98:99], v[100:101], v[108:109]
	v_pk_add_f32 v[102:103], v[102:103], v[102:103] op_sel:[0,1] op_sel_hi:[1,0]
	v_pk_fma_f32 v[156:157], v[106:107], v[104:105], v[98:99]
	s_nop 0
	v_pk_add_f32 v[158:159], v[156:157], v[102:103]
	v_mov_b32_e32 v98, v248
	v_mov_b32_e32 v99, v249
	v_mov_b32_e32 v100, v250
	v_mov_b32_e32 v101, v251
	global_load_dwordx4 v[102:105], v[110:111], off offset:768
	global_load_dwordx4 v[106:109], v[110:111], off offset:912
	s_nop 0
	global_load_dwordx4 v[110:113], v[110:111], off offset:896
	s_waitcnt vmcnt(0)
	v_mul_f32_e32 v135, v112, v0
	v_and_b32_e32 v0, 0xffff0000, v67
	v_mul_f32_e32 v195, v113, v0
	v_lshlrev_b32_e32 v0, 16, v69
	v_mul_f32_e32 v198, v108, v0
	v_and_b32_e32 v0, 0xffff0000, v69
	v_mul_f32_e32 v199, v109, v0
	v_mul_f32_e32 v0, v103, v163
	v_pk_fma_f32 v[102:103], v[102:103], v[162:163], v[0:1] op_sel_hi:[1,1,0]
	v_mul_f32_e32 v0, v105, v161
	v_mov_b32_e32 v113, v110
	v_mov_b32_e32 v110, v99
	v_pk_fma_f32 v[104:105], v[104:105], v[160:161], v[0:1] op_sel_hi:[1,1,0]
	v_lshlrev_b32_e32 v109, 16, v66
	v_lshlrev_b32_e32 v108, 16, v72
	v_mov_b32_e32 v112, v98
	v_pk_mul_f32 v[98:99], v[110:111], v[196:197]
	v_mov_b32_e32 v103, v135
	v_mov_b32_e32 v105, v195
	v_pk_fma_f32 v[98:99], v[112:113], v[108:109], v[98:99]
	v_pk_add_f32 v[102:103], v[102:103], v[104:105]
	v_mov_b32_e32 v109, v106
	v_pk_add_f32 v[98:99], v[98:99], v[102:103]
	v_pk_mov_b32 v[102:103], v[72:73], v[68:69] op_sel:[1,0]
	v_mov_b32_e32 v106, v101
	v_and_b32_e32 v103, 0xffff0000, v103
	v_and_b32_e32 v102, 0xffff0000, v102
	v_lshlrev_b32_e32 v105, 16, v68
	v_lshlrev_b32_e32 v104, 16, v73
	v_mov_b32_e32 v108, v100
	v_pk_mul_f32 v[100:101], v[106:107], v[102:103]
	v_pk_add_f32 v[102:103], v[156:157], v[158:159] op_sel:[1,0] op_sel_hi:[0,1]
	v_pk_fma_f32 v[100:101], v[108:109], v[104:105], v[100:101]
	v_mov_b32_e32 v103, v199
	v_pk_add_f32 v[98:99], v[100:101], v[98:99]
	v_pk_add_f32 v[100:101], v[154:155], v[154:155] op_sel:[0,1] op_sel_hi:[1,0]
	s_nop 0
	v_mov_b32_e32 v101, v198
	v_pk_add_f32 v[100:101], v[100:101], v[102:103]
	s_nop 0
	v_pk_add_f32 v[98:99], v[100:101], v[98:99]
	s_nop 0
	v_add_f32_e32 v0, v98, v99
	ds_bpermute_b32 v98, v171, v0
	s_waitcnt lgkmcnt(0)
	v_add_f32_e32 v0, v0, v98
	ds_bpermute_b32 v98, v170, v0
	s_waitcnt lgkmcnt(0)
	v_add_f32_e32 v154, v0, v98
